# EpiGU R1 stores write-through (sc1) so the end-of-phase L2 write-back is short
# speedup vs baseline: 1.0086x; 1.0013x over previous
.LBB0_815:
	v_lshl_add_u32 v150, s49, 10, v146
	ds_read2_b32 v[142:143], v150 offset1:16
	v_lshl_or_b32 v140, s31, 7, v147
	v_lshl_add_u32 v149, s30, 8, v144
	v_ashrrev_i32_e32 v141, 31, v140
	s_movk_i32 s15, 0x1600
	s_waitcnt lgkmcnt(0)
	v_pk_mul_f32 v[126:127], v[126:127], v[142:143] op_sel_hi:[1,0]
	v_pk_mul_f32 v[122:123], v[122:123], v[142:143] op_sel_hi:[1,0]
	v_mul_f32_e32 v151, 0xbfb8aa3b, v126
	v_exp_f32_e32 v151, v151
	v_pk_mul_f32 v[124:125], v[124:125], v[142:143] op_sel_hi:[1,0]
	v_pk_mul_f32 v[118:119], v[118:119], v[142:143] op_sel_hi:[1,0]
	v_pk_mul_f32 v[114:115], v[114:115], v[142:143] op_sel_hi:[1,0]
	v_add_f32_e32 v151, 1.0, v151
	v_rcp_f32_e32 v152, v151
	v_mul_f32_e32 v151, 0xbfb8aa3b, v127
	v_exp_f32_e32 v151, v151
	v_pk_mul_f32 v[116:117], v[116:117], v[142:143] op_sel_hi:[1,0]
	s_andn2_b64 vcc, exec, s[34:35]
	v_add_f32_e32 v151, 1.0, v151
	v_rcp_f32_e32 v153, v151
	s_nop 0
	v_pk_mul_f32 v[126:127], v[126:127], v[152:153]
	s_nop 0
	v_pk_mul_f32 v[122:123], v[122:123], v[126:127]
	v_pk_mul_f32 v[126:127], v[128:129], v[142:143] op_sel_hi:[1,0]
	s_nop 0
	v_mul_f32_e32 v128, 0xbfb8aa3b, v126
	v_mul_f32_e32 v129, 0xbfb8aa3b, v127
	v_exp_f32_e32 v128, v128
	v_exp_f32_e32 v129, v129
	v_add_f32_e32 v128, 1.0, v128
	v_add_f32_e32 v129, 1.0, v129
	v_rcp_f32_e32 v128, v128
	v_rcp_f32_e32 v129, v129
	s_nop 0
	v_pk_mul_f32 v[126:127], v[126:127], v[128:129]
	s_nop 0
	v_pk_mul_f32 v[124:125], v[124:125], v[126:127]
	v_mul_f32_e32 v126, 0xbfb8aa3b, v118
	v_mul_f32_e32 v127, 0xbfb8aa3b, v119
	v_exp_f32_e32 v126, v126
	v_exp_f32_e32 v127, v127
	v_add_f32_e32 v126, 1.0, v126
	v_add_f32_e32 v127, 1.0, v127
	v_rcp_f32_e32 v126, v126
	v_rcp_f32_e32 v127, v127
	s_nop 0
	v_pk_mul_f32 v[118:119], v[118:119], v[126:127]
	s_nop 0
	v_pk_mul_f32 v[114:115], v[114:115], v[118:119]
	v_pk_mul_f32 v[118:119], v[120:121], v[142:143] op_sel_hi:[1,0]
	s_nop 0
	v_mul_f32_e32 v120, 0xbfb8aa3b, v118
	v_mul_f32_e32 v121, 0xbfb8aa3b, v119
	v_exp_f32_e32 v120, v120
	v_exp_f32_e32 v121, v121
	v_add_f32_e32 v120, 1.0, v120
	v_add_f32_e32 v121, 1.0, v121
	v_rcp_f32_e32 v120, v120
	v_rcp_f32_e32 v121, v121
	s_nop 0
	v_pk_mul_f32 v[118:119], v[118:119], v[120:121]
	s_nop 0
	v_pk_mul_f32 v[116:117], v[116:117], v[118:119]
	v_cvt_pk_bf16_f32 v120, v114, v115
	v_mov_b64_e32 v[114:115], s[10:11]
	v_cvt_pk_bf16_f32 v118, v122, v123
	v_cvt_pk_bf16_f32 v121, v116, v117
	v_mad_i64_i32 v[122:123], s[30:31], v149, s15, v[114:115]
	v_lshlrev_b64 v[116:117], 1, v[140:141]
	v_cvt_pk_bf16_f32 v119, v124, v125
	v_lshl_add_u64 v[122:123], v[122:123], 0, v[116:117]
	global_store_dwordx4 v[122:123], v[118:121], off sc1
	s_nop 1
	v_mov_b32_e32 v118, v143
	v_pk_mul_f32 v[110:111], v[110:111], v[118:119] op_sel_hi:[1,0]
	s_nop 0
	v_mul_f32_e32 v119, 0xbfb8aa3b, v110
	v_exp_f32_e32 v119, v119
	s_nop 0
	v_add_f32_e32 v119, 1.0, v119
	v_rcp_f32_e32 v120, v119
	v_pk_mul_f32 v[106:107], v[106:107], v[118:119] op_sel_hi:[1,0]
	v_mul_f32_e32 v119, 0xbfb8aa3b, v111
	v_exp_f32_e32 v119, v119
	s_nop 0
	v_add_f32_e32 v119, 1.0, v119
	v_rcp_f32_e32 v121, v119
	v_pk_mul_f32 v[108:109], v[108:109], v[118:119] op_sel_hi:[1,0]
	v_pk_mul_f32 v[102:103], v[102:103], v[118:119] op_sel_hi:[1,0]
	v_pk_mul_f32 v[98:99], v[98:99], v[118:119] op_sel_hi:[1,0]
	v_pk_mul_f32 v[110:111], v[110:111], v[120:121]
	v_pk_mul_f32 v[100:101], v[100:101], v[118:119] op_sel_hi:[1,0]
	v_pk_mul_f32 v[106:107], v[106:107], v[110:111]
	v_pk_mul_f32 v[110:111], v[112:113], v[118:119] op_sel_hi:[1,0]
	s_nop 0
	v_mul_f32_e32 v112, 0xbfb8aa3b, v110
	v_mul_f32_e32 v113, 0xbfb8aa3b, v111
	v_exp_f32_e32 v112, v112
	v_exp_f32_e32 v113, v113
	v_add_f32_e32 v112, 1.0, v112
	v_add_f32_e32 v113, 1.0, v113
	v_rcp_f32_e32 v112, v112
	v_rcp_f32_e32 v113, v113
	s_nop 0
	v_pk_mul_f32 v[110:111], v[110:111], v[112:113]
	s_nop 0
	v_pk_mul_f32 v[108:109], v[108:109], v[110:111]
	v_mul_f32_e32 v110, 0xbfb8aa3b, v102
	v_mul_f32_e32 v111, 0xbfb8aa3b, v103
	v_exp_f32_e32 v110, v110
	v_exp_f32_e32 v111, v111
	v_add_f32_e32 v110, 1.0, v110
	v_add_f32_e32 v111, 1.0, v111
	v_rcp_f32_e32 v110, v110
	v_rcp_f32_e32 v111, v111
	s_nop 0
	v_pk_mul_f32 v[102:103], v[102:103], v[110:111]
	s_nop 0
	v_pk_mul_f32 v[102:103], v[98:99], v[102:103]
	v_pk_mul_f32 v[98:99], v[104:105], v[118:119] op_sel_hi:[1,0]
	v_or_b32_e32 v110, 16, v149
	v_mul_f32_e32 v104, 0xbfb8aa3b, v98
	v_mul_f32_e32 v105, 0xbfb8aa3b, v99
	v_exp_f32_e32 v104, v104
	v_exp_f32_e32 v105, v105
	v_add_f32_e32 v104, 1.0, v104
	v_add_f32_e32 v105, 1.0, v105
	v_rcp_f32_e32 v104, v104
	v_rcp_f32_e32 v105, v105
	s_nop 0
	v_pk_mul_f32 v[98:99], v[98:99], v[104:105]
	s_nop 0
	v_pk_mul_f32 v[104:105], v[100:101], v[98:99]
	v_cvt_pk_bf16_f32 v100, v102, v103
	v_mad_i64_i32 v[102:103], s[30:31], v110, s15, v[114:115]
	v_cvt_pk_bf16_f32 v98, v106, v107
	v_cvt_pk_bf16_f32 v99, v108, v109
	v_cvt_pk_bf16_f32 v101, v104, v105
	v_lshl_add_u64 v[102:103], v[102:103], 0, v[116:117]
	global_store_dwordx4 v[102:103], v[98:101], off sc1
	ds_read2_b32 v[98:99], v150 offset0:32 offset1:48
	s_waitcnt lgkmcnt(0)
	v_pk_mul_f32 v[94:95], v[94:95], v[98:99] op_sel_hi:[1,0]
	s_nop 0
	v_mul_f32_e32 v100, 0xbfb8aa3b, v94
	v_mul_f32_e32 v101, 0xbfb8aa3b, v95
	v_exp_f32_e32 v100, v100
	v_exp_f32_e32 v101, v101
	v_pk_mul_f32 v[90:91], v[90:91], v[98:99] op_sel_hi:[1,0]
	v_pk_mul_f32 v[92:93], v[92:93], v[98:99] op_sel_hi:[1,0]
	v_add_f32_e32 v100, 1.0, v100
	v_add_f32_e32 v101, 1.0, v101
	v_rcp_f32_e32 v100, v100
	v_rcp_f32_e32 v101, v101
	v_pk_mul_f32 v[86:87], v[86:87], v[98:99] op_sel_hi:[1,0]
	v_pk_mul_f32 v[82:83], v[82:83], v[98:99] op_sel_hi:[1,0]
	v_pk_mul_f32 v[84:85], v[84:85], v[98:99] op_sel_hi:[1,0]
	v_pk_mul_f32 v[94:95], v[94:95], v[100:101]
	s_nop 0
	v_pk_mul_f32 v[90:91], v[90:91], v[94:95]
	v_pk_mul_f32 v[94:95], v[96:97], v[98:99] op_sel_hi:[1,0]
	s_nop 0
	v_mul_f32_e32 v96, 0xbfb8aa3b, v94
	v_mul_f32_e32 v97, 0xbfb8aa3b, v95
	v_exp_f32_e32 v96, v96
	v_exp_f32_e32 v97, v97
	v_add_f32_e32 v96, 1.0, v96
	v_add_f32_e32 v97, 1.0, v97
	v_rcp_f32_e32 v96, v96
	v_rcp_f32_e32 v97, v97
	s_nop 0
	v_pk_mul_f32 v[94:95], v[94:95], v[96:97]
	s_nop 0
	v_pk_mul_f32 v[92:93], v[92:93], v[94:95]
	v_mul_f32_e32 v94, 0xbfb8aa3b, v86
	v_mul_f32_e32 v95, 0xbfb8aa3b, v87
	v_exp_f32_e32 v94, v94
	v_exp_f32_e32 v95, v95
	v_add_f32_e32 v94, 1.0, v94
	v_add_f32_e32 v95, 1.0, v95
	v_rcp_f32_e32 v94, v94
	v_rcp_f32_e32 v95, v95
	s_nop 0
	v_pk_mul_f32 v[86:87], v[86:87], v[94:95]
	s_nop 0
	v_pk_mul_f32 v[86:87], v[82:83], v[86:87]
	v_pk_mul_f32 v[82:83], v[88:89], v[98:99] op_sel_hi:[1,0]
	v_or_b32_e32 v94, 32, v149
	v_mul_f32_e32 v88, 0xbfb8aa3b, v82
	v_mul_f32_e32 v89, 0xbfb8aa3b, v83
	v_exp_f32_e32 v88, v88
	v_exp_f32_e32 v89, v89
	v_add_f32_e32 v88, 1.0, v88
	v_add_f32_e32 v89, 1.0, v89
	v_rcp_f32_e32 v88, v88
	v_rcp_f32_e32 v89, v89
	s_nop 0
	v_pk_mul_f32 v[82:83], v[82:83], v[88:89]
	s_nop 0
	v_pk_mul_f32 v[88:89], v[84:85], v[82:83]
	v_cvt_pk_bf16_f32 v84, v86, v87
	v_mad_i64_i32 v[86:87], s[30:31], v94, s15, v[114:115]
	v_cvt_pk_bf16_f32 v82, v90, v91
	v_cvt_pk_bf16_f32 v83, v92, v93
	v_cvt_pk_bf16_f32 v85, v88, v89
	v_lshl_add_u64 v[86:87], v[86:87], 0, v[116:117]
	global_store_dwordx4 v[86:87], v[82:85], off sc1
	s_nop 1
	v_mov_b32_e32 v82, v99
	v_pk_mul_f32 v[78:79], v[78:79], v[82:83] op_sel_hi:[1,0]
	s_nop 0
	v_mul_f32_e32 v83, 0xbfb8aa3b, v78
	v_exp_f32_e32 v83, v83
	s_nop 0
	v_add_f32_e32 v83, 1.0, v83
	v_rcp_f32_e32 v84, v83
	v_pk_mul_f32 v[74:75], v[74:75], v[82:83] op_sel_hi:[1,0]
	v_mul_f32_e32 v83, 0xbfb8aa3b, v79
	v_exp_f32_e32 v83, v83
	s_nop 0
	v_add_f32_e32 v83, 1.0, v83
	v_rcp_f32_e32 v85, v83
	v_pk_mul_f32 v[76:77], v[76:77], v[82:83] op_sel_hi:[1,0]
	v_pk_mul_f32 v[70:71], v[70:71], v[82:83] op_sel_hi:[1,0]
	v_pk_mul_f32 v[66:67], v[66:67], v[82:83] op_sel_hi:[1,0]
	v_pk_mul_f32 v[78:79], v[78:79], v[84:85]
	v_pk_mul_f32 v[68:69], v[68:69], v[82:83] op_sel_hi:[1,0]
	v_pk_mul_f32 v[74:75], v[74:75], v[78:79]
	v_pk_mul_f32 v[78:79], v[80:81], v[82:83] op_sel_hi:[1,0]
	s_nop 0
	v_mul_f32_e32 v80, 0xbfb8aa3b, v78
	v_mul_f32_e32 v81, 0xbfb8aa3b, v79
	v_exp_f32_e32 v80, v80
	v_exp_f32_e32 v81, v81
	v_add_f32_e32 v80, 1.0, v80
	v_add_f32_e32 v81, 1.0, v81
	v_rcp_f32_e32 v80, v80
	v_rcp_f32_e32 v81, v81
	s_nop 0
	v_pk_mul_f32 v[78:79], v[78:79], v[80:81]
	s_nop 0
	v_pk_mul_f32 v[76:77], v[76:77], v[78:79]
	v_mul_f32_e32 v78, 0xbfb8aa3b, v70
	v_mul_f32_e32 v79, 0xbfb8aa3b, v71
	v_exp_f32_e32 v78, v78
	v_exp_f32_e32 v79, v79
	v_add_f32_e32 v78, 1.0, v78
	v_add_f32_e32 v79, 1.0, v79
	v_rcp_f32_e32 v78, v78
	v_rcp_f32_e32 v79, v79
	s_nop 0
	v_pk_mul_f32 v[70:71], v[70:71], v[78:79]
	s_nop 0
	v_pk_mul_f32 v[70:71], v[66:67], v[70:71]
	v_pk_mul_f32 v[66:67], v[72:73], v[82:83] op_sel_hi:[1,0]
	v_or_b32_e32 v78, 48, v149
	v_mul_f32_e32 v72, 0xbfb8aa3b, v66
	v_mul_f32_e32 v73, 0xbfb8aa3b, v67
	v_exp_f32_e32 v72, v72
	v_exp_f32_e32 v73, v73
	v_add_f32_e32 v72, 1.0, v72
	v_add_f32_e32 v73, 1.0, v73
	v_rcp_f32_e32 v72, v72
	v_rcp_f32_e32 v73, v73
	s_nop 0
	v_pk_mul_f32 v[66:67], v[66:67], v[72:73]
	s_nop 0
	v_pk_mul_f32 v[72:73], v[68:69], v[66:67]
	v_cvt_pk_bf16_f32 v68, v70, v71
	v_mad_i64_i32 v[70:71], s[30:31], v78, s15, v[114:115]
	v_cvt_pk_bf16_f32 v66, v74, v75
	v_cvt_pk_bf16_f32 v67, v76, v77
	v_cvt_pk_bf16_f32 v69, v72, v73
	v_lshl_add_u64 v[70:71], v[70:71], 0, v[116:117]
	global_store_dwordx4 v[70:71], v[66:69], off sc1
	ds_read2_b32 v[66:67], v150 offset0:128 offset1:144
	v_add_u32_e32 v70, 0x80, v149
	s_waitcnt lgkmcnt(0)
	v_pk_mul_f32 v[62:63], v[62:63], v[66:67] op_sel_hi:[1,0]
	s_nop 0
	v_mul_f32_e32 v68, 0xbfb8aa3b, v62
	v_mul_f32_e32 v69, 0xbfb8aa3b, v63
	v_exp_f32_e32 v68, v68
	v_exp_f32_e32 v69, v69
	v_pk_mul_f32 v[58:59], v[58:59], v[66:67] op_sel_hi:[1,0]
	v_pk_mul_f32 v[60:61], v[60:61], v[66:67] op_sel_hi:[1,0]
	v_add_f32_e32 v68, 1.0, v68
	v_add_f32_e32 v69, 1.0, v69
	v_rcp_f32_e32 v68, v68
	v_rcp_f32_e32 v69, v69
	v_pk_mul_f32 v[54:55], v[54:55], v[66:67] op_sel_hi:[1,0]
	v_pk_mul_f32 v[50:51], v[50:51], v[66:67] op_sel_hi:[1,0]
	v_pk_mul_f32 v[52:53], v[52:53], v[66:67] op_sel_hi:[1,0]
	v_pk_mul_f32 v[62:63], v[62:63], v[68:69]
	s_nop 0
	v_pk_mul_f32 v[58:59], v[58:59], v[62:63]
	v_pk_mul_f32 v[62:63], v[64:65], v[66:67] op_sel_hi:[1,0]
	s_nop 0
	v_mul_f32_e32 v64, 0xbfb8aa3b, v62
	v_mul_f32_e32 v65, 0xbfb8aa3b, v63
	v_exp_f32_e32 v64, v64
	v_exp_f32_e32 v65, v65
	v_add_f32_e32 v64, 1.0, v64
	v_add_f32_e32 v65, 1.0, v65
	v_rcp_f32_e32 v64, v64
	v_rcp_f32_e32 v65, v65
	s_nop 0
	v_pk_mul_f32 v[62:63], v[62:63], v[64:65]
	s_nop 0
	v_pk_mul_f32 v[60:61], v[60:61], v[62:63]
	v_mul_f32_e32 v62, 0xbfb8aa3b, v54
	v_mul_f32_e32 v63, 0xbfb8aa3b, v55
	v_exp_f32_e32 v62, v62
	v_exp_f32_e32 v63, v63
	v_add_f32_e32 v62, 1.0, v62
	v_add_f32_e32 v63, 1.0, v63
	v_rcp_f32_e32 v62, v62
	v_rcp_f32_e32 v63, v63
	s_nop 0
	v_pk_mul_f32 v[54:55], v[54:55], v[62:63]
	s_nop 0
	v_pk_mul_f32 v[54:55], v[50:51], v[54:55]
	v_pk_mul_f32 v[50:51], v[56:57], v[66:67] op_sel_hi:[1,0]
	s_nop 0
	v_mul_f32_e32 v56, 0xbfb8aa3b, v50
	v_mul_f32_e32 v57, 0xbfb8aa3b, v51
	v_exp_f32_e32 v56, v56
	v_exp_f32_e32 v57, v57
	v_add_f32_e32 v56, 1.0, v56
	v_add_f32_e32 v57, 1.0, v57
	v_rcp_f32_e32 v56, v56
	v_rcp_f32_e32 v57, v57
	s_nop 0
	v_pk_mul_f32 v[50:51], v[50:51], v[56:57]
	s_nop 0
	v_pk_mul_f32 v[56:57], v[52:53], v[50:51]
	v_cvt_pk_bf16_f32 v52, v54, v55
	v_mad_i64_i32 v[54:55], s[30:31], v70, s15, v[114:115]
	v_cvt_pk_bf16_f32 v50, v58, v59
	v_cvt_pk_bf16_f32 v51, v60, v61
	v_cvt_pk_bf16_f32 v53, v56, v57
	v_lshl_add_u64 v[54:55], v[54:55], 0, v[116:117]
	global_store_dwordx4 v[54:55], v[50:53], off sc1
	s_nop 1
	v_mov_b32_e32 v50, v67
	v_pk_mul_f32 v[46:47], v[46:47], v[50:51] op_sel_hi:[1,0]
	s_nop 0
	v_mul_f32_e32 v51, 0xbfb8aa3b, v46
	v_exp_f32_e32 v51, v51
	s_nop 0
	v_add_f32_e32 v51, 1.0, v51
	v_rcp_f32_e32 v52, v51
	v_pk_mul_f32 v[42:43], v[42:43], v[50:51] op_sel_hi:[1,0]
	v_mul_f32_e32 v51, 0xbfb8aa3b, v47
	v_exp_f32_e32 v51, v51
	s_nop 0
	v_add_f32_e32 v51, 1.0, v51
	v_rcp_f32_e32 v53, v51
	v_pk_mul_f32 v[44:45], v[44:45], v[50:51] op_sel_hi:[1,0]
	v_pk_mul_f32 v[38:39], v[38:39], v[50:51] op_sel_hi:[1,0]
	v_pk_mul_f32 v[34:35], v[34:35], v[50:51] op_sel_hi:[1,0]
	v_pk_mul_f32 v[46:47], v[46:47], v[52:53]
	v_pk_mul_f32 v[36:37], v[36:37], v[50:51] op_sel_hi:[1,0]
	v_pk_mul_f32 v[42:43], v[42:43], v[46:47]
	v_pk_mul_f32 v[46:47], v[48:49], v[50:51] op_sel_hi:[1,0]
	s_nop 0
	v_mul_f32_e32 v48, 0xbfb8aa3b, v46
	v_mul_f32_e32 v49, 0xbfb8aa3b, v47
	v_exp_f32_e32 v48, v48
	v_exp_f32_e32 v49, v49
	v_add_f32_e32 v48, 1.0, v48
	v_add_f32_e32 v49, 1.0, v49
	v_rcp_f32_e32 v48, v48
	v_rcp_f32_e32 v49, v49
	s_nop 0
	v_pk_mul_f32 v[46:47], v[46:47], v[48:49]
	s_nop 0
	v_pk_mul_f32 v[44:45], v[44:45], v[46:47]
	v_mul_f32_e32 v46, 0xbfb8aa3b, v38
	v_mul_f32_e32 v47, 0xbfb8aa3b, v39
	v_exp_f32_e32 v46, v46
	v_exp_f32_e32 v47, v47
	v_add_f32_e32 v46, 1.0, v46
	v_add_f32_e32 v47, 1.0, v47
	v_rcp_f32_e32 v46, v46
	v_rcp_f32_e32 v47, v47
	s_nop 0
	v_pk_mul_f32 v[38:39], v[38:39], v[46:47]
	s_nop 0
	v_pk_mul_f32 v[38:39], v[34:35], v[38:39]
	v_pk_mul_f32 v[34:35], v[40:41], v[50:51] op_sel_hi:[1,0]
	v_add_u32_e32 v46, 0x90, v149
	v_mul_f32_e32 v40, 0xbfb8aa3b, v34
	v_mul_f32_e32 v41, 0xbfb8aa3b, v35
	v_exp_f32_e32 v40, v40
	v_exp_f32_e32 v41, v41
	v_add_f32_e32 v40, 1.0, v40
	v_add_f32_e32 v41, 1.0, v41
	v_rcp_f32_e32 v40, v40
	v_rcp_f32_e32 v41, v41
	s_nop 0
	v_pk_mul_f32 v[34:35], v[34:35], v[40:41]
	s_nop 0
	v_pk_mul_f32 v[40:41], v[36:37], v[34:35]
	v_cvt_pk_bf16_f32 v36, v38, v39
	v_mad_i64_i32 v[38:39], s[30:31], v46, s15, v[114:115]
	v_cvt_pk_bf16_f32 v34, v42, v43
	v_cvt_pk_bf16_f32 v35, v44, v45
	v_cvt_pk_bf16_f32 v37, v40, v41
	v_lshl_add_u64 v[38:39], v[38:39], 0, v[116:117]
	global_store_dwordx4 v[38:39], v[34:37], off sc1
	ds_read2_b32 v[34:35], v150 offset0:160 offset1:176
	s_waitcnt lgkmcnt(0)
	v_pk_mul_f32 v[30:31], v[30:31], v[34:35] op_sel_hi:[1,0]
	s_nop 0
	v_mul_f32_e32 v36, 0xbfb8aa3b, v30
	v_mul_f32_e32 v37, 0xbfb8aa3b, v31
	v_exp_f32_e32 v36, v36
	v_exp_f32_e32 v37, v37
	v_pk_mul_f32 v[26:27], v[26:27], v[34:35] op_sel_hi:[1,0]
	v_pk_mul_f32 v[28:29], v[28:29], v[34:35] op_sel_hi:[1,0]
	v_add_f32_e32 v36, 1.0, v36
	v_add_f32_e32 v37, 1.0, v37
	v_rcp_f32_e32 v36, v36
	v_rcp_f32_e32 v37, v37
	v_pk_mul_f32 v[22:23], v[22:23], v[34:35] op_sel_hi:[1,0]
	v_pk_mul_f32 v[18:19], v[18:19], v[34:35] op_sel_hi:[1,0]
	v_pk_mul_f32 v[20:21], v[20:21], v[34:35] op_sel_hi:[1,0]
	v_pk_mul_f32 v[30:31], v[30:31], v[36:37]
	s_nop 0
	v_pk_mul_f32 v[26:27], v[26:27], v[30:31]
	v_pk_mul_f32 v[30:31], v[32:33], v[34:35] op_sel_hi:[1,0]
	s_nop 0
	v_mul_f32_e32 v32, 0xbfb8aa3b, v30
	v_mul_f32_e32 v33, 0xbfb8aa3b, v31
	v_exp_f32_e32 v32, v32
	v_exp_f32_e32 v33, v33
	v_add_f32_e32 v32, 1.0, v32
	v_add_f32_e32 v33, 1.0, v33
	v_rcp_f32_e32 v32, v32
	v_rcp_f32_e32 v33, v33
	s_nop 0
	v_pk_mul_f32 v[30:31], v[30:31], v[32:33]
	s_nop 0
	v_pk_mul_f32 v[28:29], v[28:29], v[30:31]
	v_mul_f32_e32 v30, 0xbfb8aa3b, v22
	v_mul_f32_e32 v31, 0xbfb8aa3b, v23
	v_exp_f32_e32 v30, v30
	v_exp_f32_e32 v31, v31
	v_add_f32_e32 v30, 1.0, v30
	v_add_f32_e32 v31, 1.0, v31
	v_rcp_f32_e32 v30, v30
	v_rcp_f32_e32 v31, v31
	s_nop 0
	v_pk_mul_f32 v[22:23], v[22:23], v[30:31]
	s_nop 0
	v_pk_mul_f32 v[22:23], v[18:19], v[22:23]
	v_pk_mul_f32 v[18:19], v[24:25], v[34:35] op_sel_hi:[1,0]
	v_add_u32_e32 v30, 0xa0, v149
	v_mul_f32_e32 v24, 0xbfb8aa3b, v18
	v_mul_f32_e32 v25, 0xbfb8aa3b, v19
	v_exp_f32_e32 v24, v24
	v_exp_f32_e32 v25, v25
	v_add_f32_e32 v24, 1.0, v24
	v_add_f32_e32 v25, 1.0, v25
	v_rcp_f32_e32 v24, v24
	v_rcp_f32_e32 v25, v25
	s_nop 0
	v_pk_mul_f32 v[18:19], v[18:19], v[24:25]
	s_nop 0
	v_pk_mul_f32 v[24:25], v[20:21], v[18:19]
	v_cvt_pk_bf16_f32 v20, v22, v23
	v_mad_i64_i32 v[22:23], s[30:31], v30, s15, v[114:115]
	v_cvt_pk_bf16_f32 v18, v26, v27
	v_cvt_pk_bf16_f32 v19, v28, v29
	v_cvt_pk_bf16_f32 v21, v24, v25
	v_lshl_add_u64 v[22:23], v[22:23], 0, v[116:117]
	global_store_dwordx4 v[22:23], v[18:21], off sc1
	s_nop 1
	v_mov_b32_e32 v18, v35
	v_pk_mul_f32 v[14:15], v[14:15], v[18:19] op_sel_hi:[1,0]
	s_nop 0
	v_mul_f32_e32 v19, 0xbfb8aa3b, v14
	v_exp_f32_e32 v19, v19
	s_nop 0
	v_add_f32_e32 v19, 1.0, v19
	v_rcp_f32_e32 v20, v19
	v_pk_mul_f32 v[10:11], v[10:11], v[18:19] op_sel_hi:[1,0]
	v_mul_f32_e32 v19, 0xbfb8aa3b, v15
	v_exp_f32_e32 v19, v19
	s_nop 0
	v_add_f32_e32 v19, 1.0, v19
	v_rcp_f32_e32 v21, v19
	v_pk_mul_f32 v[12:13], v[12:13], v[18:19] op_sel_hi:[1,0]
	v_pk_mul_f32 v[6:7], v[6:7], v[18:19] op_sel_hi:[1,0]
	v_pk_mul_f32 v[2:3], v[2:3], v[18:19] op_sel_hi:[1,0]
	v_pk_mul_f32 v[14:15], v[14:15], v[20:21]
	v_pk_mul_f32 v[4:5], v[4:5], v[18:19] op_sel_hi:[1,0]
	v_pk_mul_f32 v[10:11], v[10:11], v[14:15]
	v_pk_mul_f32 v[14:15], v[16:17], v[18:19] op_sel_hi:[1,0]
	s_nop 0
	v_mul_f32_e32 v16, 0xbfb8aa3b, v14
	v_mul_f32_e32 v17, 0xbfb8aa3b, v15
	v_exp_f32_e32 v16, v16
	v_exp_f32_e32 v17, v17
	v_add_f32_e32 v16, 1.0, v16
	v_add_f32_e32 v17, 1.0, v17
	v_rcp_f32_e32 v16, v16
	v_rcp_f32_e32 v17, v17
	s_nop 0
	v_pk_mul_f32 v[14:15], v[14:15], v[16:17]
	s_nop 0
	v_pk_mul_f32 v[12:13], v[12:13], v[14:15]
	v_mul_f32_e32 v14, 0xbfb8aa3b, v6
	v_mul_f32_e32 v15, 0xbfb8aa3b, v7
	v_exp_f32_e32 v14, v14
	v_exp_f32_e32 v15, v15
	v_add_f32_e32 v14, 1.0, v14
	v_add_f32_e32 v15, 1.0, v15
	v_rcp_f32_e32 v14, v14
	v_rcp_f32_e32 v15, v15
	s_nop 0
	v_pk_mul_f32 v[6:7], v[6:7], v[14:15]
	s_nop 0
	v_pk_mul_f32 v[6:7], v[2:3], v[6:7]
	v_pk_mul_f32 v[2:3], v[8:9], v[18:19] op_sel_hi:[1,0]
	v_add_u32_e32 v14, 0xb0, v149
	v_mul_f32_e32 v8, 0xbfb8aa3b, v2
	v_mul_f32_e32 v9, 0xbfb8aa3b, v3
	v_exp_f32_e32 v8, v8
	v_exp_f32_e32 v9, v9
	v_add_f32_e32 v8, 1.0, v8
	v_add_f32_e32 v9, 1.0, v9
	v_rcp_f32_e32 v8, v8
	v_rcp_f32_e32 v9, v9
	s_nop 0
	v_pk_mul_f32 v[2:3], v[2:3], v[8:9]
	s_nop 0
	v_pk_mul_f32 v[8:9], v[4:5], v[2:3]
	v_cvt_pk_bf16_f32 v4, v6, v7
	v_mad_i64_i32 v[6:7], s[30:31], v14, s15, v[114:115]
	v_cvt_pk_bf16_f32 v2, v10, v11
	v_cvt_pk_bf16_f32 v3, v12, v13
	v_cvt_pk_bf16_f32 v5, v8, v9
	v_lshl_add_u64 v[6:7], v[6:7], 0, v[116:117]
	s_mov_b64 s[30:31], -1
	global_store_dwordx4 v[6:7], v[2:5], off sc1
	s_cbranch_vccnz .LBB0_808
	s_andn2_b64 vcc, exec, s[8:9]
	s_cbranch_vccnz .LBB0_807
	s_barrier
	s_branch .LBB0_807
